# phase 1: nt hint on the bf16 residual-copy (zb) stores, not needed until the out-proj epilogue
# speedup vs baseline: 1.0155x; 1.0090x over previous
; __device__ __forceinline__ unsigned cvt_pk_bf16(float lo, float hi) { unsigned r; asm volatile("v_cvt_pk_bf16_f32 %0, %1, %2" : "=v"(r) : "v"(lo), "v"(hi)); return r; }
; template <bool DO_LN>
; __device__ __forceinline__ void row_phase(const float* xin, bf16_t* zb, float* xout, const float* g, const float* bta, const float* modl, int sc_off, int sh_off, bf16_t* U, float* stats, int rbase) {
;     ...
;         if (U) {
;             if (!DO_LN) {
;                 const unsigned voff = (unsigned)lane * 16u;
;                 const char* mb = (const char*)(modl + (size_t)(row >> 12) * (6 * DM));
; #pragma unroll
;                 for (int i = 0; i < 8; ++i) { scv[i] = *(const f32x4*)(mb + ((unsigned)sc_off * 4u + voff + (unsigned)i * 1024u)); shv[i] = *(const f32x4*)(mb + ((unsigned)sh_off * 4u + voff + (unsigned)i * 1024u)); }
;             }
; #pragma unroll
;             for (int i = 0; i < 8; ++i) {
;                 const f32x4 uu = v[i] * (scv[i] + 1.0f) + shv[i];
;                 u32x2 w; w.x = cvt_pk_bf16(uu[0], uu[1]); w.y = cvt_pk_bf16(uu[2], uu[3]);
;                 *(u32x2*)(U + pg8::tiled_off(row, i * 256 + lane * 4, DM / 64)) = w;
;                 if (!DO_LN) { u32x2 wz; wz.x = cvt_pk_bf16(v[i][0], v[i][1]); wz.y = cvt_pk_bf16(v[i][2], v[i][3]); *(u32x2*)(zb + (size_t)row * DM + lane * 4 + i * 256) = wz; }
;             }
.LBB0_318:
	s_or_b64 exec, exec, s[10:11]
	v_ashrrev_i32_e32 v60, 12, v104
	v_mul_hi_i32_i24_e32 v61, 0xc000, v60
	v_mul_i32_i24_e32 v60, 0xc000, v60
	v_lshl_add_u64 v[60:61], v[98:99], 0, v[60:61]
	s_movk_i32 s7, 0x3000
	v_add_co_u32_e32 v128, vcc, s7, v60
	s_movk_i32 s7, 0x2000
	s_nop 0
	v_addc_co_u32_e32 v129, vcc, 0, v61, vcc
	global_load_dwordx4 v[68:71], v[128:129], off offset:-4096
	global_load_dwordx4 v[72:75], v[60:61], off
	v_add_co_u32_e32 v62, vcc, s7, v60
	s_movk_i32 s7, 0x1000
	s_nop 0
	v_addc_co_u32_e32 v63, vcc, 0, v61, vcc
	global_load_dwordx4 v[76:79], v[62:63], off offset:1024
	global_load_dwordx4 v[84:87], v[60:61], off offset:1024
	global_load_dwordx4 v[106:109], v[62:63], off offset:2048
	global_load_dwordx4 v[112:115], v[60:61], off offset:2048
	global_load_dwordx4 v[120:123], v[62:63], off offset:3072
	global_load_dwordx4 v[124:127], v[60:61], off offset:3072
	v_lshrrev_b32_e32 v62, 3, v104
	v_lshrrev_b32_e32 v80, 4, v118
	v_and_or_b32 v62, v62, 14, v116
	v_add_co_u32_e32 v130, vcc, s7, v60
	v_and_or_b32 v63, v118, s22, v119
	v_and_b32_e32 v80, 32, v80
	v_lshlrev_b32_e32 v62, 10, v62
	v_addc_co_u32_e32 v131, vcc, 0, v61, vcc
	v_bitop3_b32 v152, v63, v62, v80 bitop3:0xde
	global_load_dwordx4 v[80:83], v[128:129], off
	global_load_dwordx4 v[60:63], v[130:131], off offset:3072
	global_load_dwordx4 v[92:95], v[130:131], off
	global_load_dwordx4 v[88:91], v[128:129], off offset:1024
	v_ashrrev_i32_e32 v103, 2, v104
	s_movk_i32 s7, 0xffe0
	v_readlane_b32 s10, v252, 53
	v_readlane_b32 s11, v252, 54
	s_and_b64 s[0:1], exec, s[0:1]
	s_or_b64 s[4:5], s[0:1], s[4:5]
	v_lshl_add_u64 v[104:105], s[10:11], 0, v[152:153]
	v_add_u32_e32 v118, s12, v118
	s_waitcnt vmcnt(11)
	v_pk_add_f32 v[70:71], v[70:71], 1.0 op_sel_hi:[1,0]
	v_pk_add_f32 v[68:69], v[68:69], 1.0 op_sel_hi:[1,0]
	s_waitcnt vmcnt(10)
	v_pk_fma_f32 v[132:133], v[66:67], v[70:71], v[74:75]
	v_pk_fma_f32 v[134:135], v[64:65], v[68:69], v[72:73]
	s_waitcnt vmcnt(9)
	v_pk_add_f32 v[68:69], v[78:79], 1.0 op_sel_hi:[1,0]
	v_pk_add_f32 v[70:71], v[76:77], 1.0 op_sel_hi:[1,0]
	s_waitcnt vmcnt(8)
	v_pk_fma_f32 v[136:137], v[58:59], v[68:69], v[86:87]
	v_pk_fma_f32 v[138:139], v[56:57], v[70:71], v[84:85]
	global_load_dwordx4 v[84:87], v[130:131], off offset:1024
	s_waitcnt vmcnt(8)
	v_pk_add_f32 v[68:69], v[108:109], 1.0 op_sel_hi:[1,0]
	v_pk_add_f32 v[70:71], v[106:107], 1.0 op_sel_hi:[1,0]
	s_waitcnt vmcnt(7)
	v_pk_fma_f32 v[110:111], v[54:55], v[68:69], v[114:115]
	v_pk_fma_f32 v[114:115], v[52:53], v[70:71], v[112:113]
	s_waitcnt vmcnt(6)
	v_pk_add_f32 v[68:69], v[122:123], 1.0 op_sel_hi:[1,0]
	v_pk_add_f32 v[70:71], v[120:121], 1.0 op_sel_hi:[1,0]
	s_waitcnt vmcnt(5)
	v_pk_fma_f32 v[108:109], v[50:51], v[68:69], v[126:127]
	v_pk_fma_f32 v[112:113], v[48:49], v[70:71], v[124:125]
	global_load_dwordx4 v[76:79], v[128:129], off offset:2048
	global_load_dwordx4 v[72:75], v[130:131], off offset:2048
	global_load_dwordx4 v[68:71], v[128:129], off offset:3072
	v_and_or_b32 v106, v103, s7, v117
	v_ashrrev_i32_e32 v107, 31, v106
	v_lshlrev_b64 v[122:123], 14, v[106:107]
	v_lshl_add_u64 v[122:123], v[104:105], 0, v[122:123]
	v_cvt_pk_bf16_f32 v120, v134, v135
	v_cvt_pk_bf16_f32 v121, v132, v133
	global_store_dwordx2 v[122:123], v[120:121], off
	v_cvt_pk_bf16_f32 v64, v64, v65
	v_cvt_pk_bf16_f32 v65, v66, v67
	v_or_b32_e32 v66, 4, v106
	global_store_dwordx2 v[100:101], v[64:65], off offset:-2048 nt
	v_or_b32_e32 v64, 8, v106
	v_ashrrev_i32_e32 v67, 31, v66
	v_ashrrev_i32_e32 v65, 31, v64
	v_lshlrev_b64 v[66:67], 14, v[66:67]
	v_or_b32_e32 v122, 12, v106
	v_lshlrev_b64 v[64:65], 14, v[64:65]
	v_lshl_add_u64 v[66:67], v[104:105], 0, v[66:67]
	v_cvt_pk_bf16_f32 v120, v138, v139
	v_cvt_pk_bf16_f32 v121, v136, v137
	v_ashrrev_i32_e32 v123, 31, v122
	v_lshl_add_u64 v[64:65], v[104:105], 0, v[64:65]
	global_store_dwordx2 v[66:67], v[120:121], off
	v_cvt_pk_bf16_f32 v56, v56, v57
	v_cvt_pk_bf16_f32 v57, v58, v59
	global_store_dwordx2 v[100:101], v[56:57], off offset:-1536 nt
	v_cvt_pk_bf16_f32 v56, v114, v115
	v_cvt_pk_bf16_f32 v57, v110, v111
	global_store_dwordx2 v[64:65], v[56:57], off
	v_cvt_pk_bf16_f32 v52, v52, v53
	v_cvt_pk_bf16_f32 v53, v54, v55
	v_lshlrev_b64 v[54:55], 14, v[122:123]
	v_lshl_add_u64 v[54:55], v[104:105], 0, v[54:55]
	global_store_dwordx2 v[100:101], v[52:53], off offset:-1024 nt
	v_cvt_pk_bf16_f32 v52, v112, v113
	v_cvt_pk_bf16_f32 v53, v108, v109
	global_store_dwordx2 v[54:55], v[52:53], off
	v_cvt_pk_bf16_f32 v48, v48, v49
	v_cvt_pk_bf16_f32 v49, v50, v51
	global_store_dwordx2 v[100:101], v[48:49], off offset:-512 nt
	s_waitcnt vmcnt(15)
; __device__ __forceinline__ unsigned cvt_pk_bf16(float lo, float hi) { unsigned r; asm volatile("v_cvt_pk_bf16_f32 %0, %1, %2" : "=v"(r) : "v"(lo), "v"(hi)); return r; }
; template <bool DO_LN>
; __device__ __forceinline__ void row_phase(const float* xin, bf16_t* zb, float* xout, const float* g, const float* bta, const float* modl, int sc_off, int sh_off, bf16_t* U, float* stats, int rbase) {
;     ...
;             for (int i = 0; i < 8; ++i) {
;                 const f32x4 uu = v[i] * (scv[i] + 1.0f) + shv[i];
;                 u32x2 w; w.x = cvt_pk_bf16(uu[0], uu[1]); w.y = cvt_pk_bf16(uu[2], uu[3]);
;                 *(u32x2*)(U + pg8::tiled_off(row, i * 256 + lane * 4, DM / 64)) = w;
;                 if (!DO_LN) { u32x2 wz; wz.x = cvt_pk_bf16(v[i][0], v[i][1]); wz.y = cvt_pk_bf16(v[i][2], v[i][3]); *(u32x2*)(zb + (size_t)row * DM + lane * 4 + i * 256) = wz; }
;             }
	v_pk_add_f32 v[48:49], v[82:83], 1.0 op_sel_hi:[1,0]
	v_pk_add_f32 v[50:51], v[80:81], 1.0 op_sel_hi:[1,0]
	s_waitcnt vmcnt(13)
	v_pk_fma_f32 v[48:49], v[46:47], v[48:49], v[94:95]
	v_pk_fma_f32 v[50:51], v[44:45], v[50:51], v[92:93]
	v_mov_b64_e32 v[66:67], v[10:11]
	v_cvt_pk_bf16_f32 v50, v50, v51
	v_cvt_pk_bf16_f32 v51, v48, v49
	v_or_b32_e32 v48, 16, v106
	v_ashrrev_i32_e32 v49, 31, v48
	v_lshlrev_b64 v[48:49], 14, v[48:49]
	v_lshl_add_u64 v[48:49], v[104:105], 0, v[48:49]
	global_store_dwordx2 v[48:49], v[50:51], off
	v_cvt_pk_bf16_f32 v44, v44, v45
	v_cvt_pk_bf16_f32 v45, v46, v47
	global_store_dwordx2 v[100:101], v[44:45], off nt
	s_waitcnt vmcnt(14)
	v_pk_add_f32 v[44:45], v[90:91], 1.0 op_sel_hi:[1,0]
	v_pk_add_f32 v[46:47], v[88:89], 1.0 op_sel_hi:[1,0]
	v_mov_b64_e32 v[58:59], v[14:15]
	v_mov_b64_e32 v[54:55], v[18:19]
	v_mov_b64_e32 v[50:51], v[22:23]
	v_mov_b64_e32 v[64:65], v[8:9]
	v_mov_b64_e32 v[56:57], v[12:13]
	v_mov_b64_e32 v[52:53], v[16:17]
	v_mov_b64_e32 v[48:49], v[20:21]
	s_waitcnt vmcnt(13)
	v_pk_fma_f32 v[44:45], v[42:43], v[44:45], v[86:87]
	v_pk_fma_f32 v[46:47], v[40:41], v[46:47], v[84:85]
	s_nop 0
	v_cvt_pk_bf16_f32 v46, v46, v47
	v_cvt_pk_bf16_f32 v47, v44, v45
	v_or_b32_e32 v44, 20, v106
	v_ashrrev_i32_e32 v45, 31, v44
	v_lshlrev_b64 v[44:45], 14, v[44:45]
	v_lshl_add_u64 v[44:45], v[104:105], 0, v[44:45]
	global_store_dwordx2 v[44:45], v[46:47], off
	v_cvt_pk_bf16_f32 v40, v40, v41
	v_cvt_pk_bf16_f32 v41, v42, v43
	global_store_dwordx2 v[100:101], v[40:41], off offset:512 nt
	s_waitcnt vmcnt(14)
	v_pk_add_f32 v[40:41], v[78:79], 1.0 op_sel_hi:[1,0]
	v_pk_add_f32 v[42:43], v[76:77], 1.0 op_sel_hi:[1,0]
	s_waitcnt vmcnt(13)
	v_pk_fma_f32 v[40:41], v[6:7], v[40:41], v[74:75]
	v_pk_fma_f32 v[42:43], v[4:5], v[42:43], v[72:73]
	v_mov_b64_e32 v[46:47], v[26:27]
	v_cvt_pk_bf16_f32 v42, v42, v43
	v_cvt_pk_bf16_f32 v43, v40, v41
	v_or_b32_e32 v40, 24, v106
	v_ashrrev_i32_e32 v41, 31, v40
	v_lshlrev_b64 v[40:41], 14, v[40:41]
	v_lshl_add_u64 v[40:41], v[104:105], 0, v[40:41]
	global_store_dwordx2 v[40:41], v[42:43], off
	v_cvt_pk_bf16_f32 v4, v4, v5
	v_cvt_pk_bf16_f32 v5, v6, v7
	global_store_dwordx2 v[100:101], v[4:5], off offset:1024 nt
	s_waitcnt vmcnt(14)
	v_pk_add_f32 v[4:5], v[70:71], 1.0 op_sel_hi:[1,0]
	v_pk_add_f32 v[6:7], v[68:69], 1.0 op_sel_hi:[1,0]
	v_pk_fma_f32 v[4:5], v[2:3], v[4:5], v[62:63]
	v_pk_fma_f32 v[6:7], v[0:1], v[6:7], v[60:61]
	v_mov_b64_e32 v[42:43], v[30:31]
	v_cvt_pk_bf16_f32 v6, v6, v7
	v_cvt_pk_bf16_f32 v7, v4, v5
	v_or_b32_e32 v4, 28, v106
	v_ashrrev_i32_e32 v5, 31, v4
	v_lshlrev_b64 v[4:5], 14, v[4:5]
	v_lshl_add_u64 v[4:5], v[104:105], 0, v[4:5]
	global_store_dwordx2 v[4:5], v[6:7], off
	v_cvt_pk_bf16_f32 v0, v0, v1
	v_cvt_pk_bf16_f32 v1, v2, v3
	global_store_dwordx2 v[100:101], v[0:1], off offset:1536 nt
	v_mov_b64_e32 v[4:5], v[32:33]
	v_mov_b64_e32 v[0:1], v[36:37]
	v_lshl_add_u64 v[100:101], v[100:101], 0, s[8:9]
	v_mov_b64_e32 v[44:45], v[24:25]
	v_mov_b64_e32 v[40:41], v[28:29]
	v_mov_b64_e32 v[6:7], v[34:35]
	v_mov_b64_e32 v[2:3], v[38:39]
	v_mov_b32_e32 v104, v102
	s_andn2_b64 exec, exec, s[4:5]
	s_cbranch_execz .LBB0_322
